# conv phase: nt hint on the read-once gate/h_in loads so q/k/v stay cached for attention
# baseline (speedup 1.0000x reference)
; __device__ __forceinline__ void conv_phase(const Params& p, int l, int rbase) {
;     ...
;     const int tstep = rbase >= 0 ? 8 : (int)gridDim.x * 8, tend = rbase >= 0 ? rbase + 64 : T_TOK;
;     int t = (rbase >= 0 ? rbase : (int)blockIdx.x * 8) + wid;
;     if (t < tend) CONV_LOAD(t);
.LBB0_277:
	v_add_u32_e32 v206, s15, v166
	v_cmp_gt_i32_e32 vcc, s14, v206
	v_cmp_le_i32_e64 s[0:1], s14, v206
	v_mov_b32_e32 v161, v103
	v_mov_b32_e32 v160, v102
	v_mov_b32_e32 v163, v97
	v_mov_b32_e32 v162, v96
	s_and_saveexec_b64 s[10:11], vcc
	s_cbranch_execz .LBB0_276
	s_movk_i32 s4, 0x3000
	v_mad_i64_i32 v[0:1], s[4:5], v206, s4, v[48:49]
	v_add_co_u32_e32 v2, vcc, 0x1000, v0
	v_mov_b32_e32 v90, v153
	s_nop 0
	v_addc_co_u32_e32 v3, vcc, 0, v1, vcc
	v_add_co_u32_e32 v4, vcc, 0x2000, v0
	v_mov_b32_e32 v91, v153
	s_nop 0
	v_addc_co_u32_e32 v5, vcc, 0, v1, vcc
	global_load_dwordx2 v[76:77], v[2:3], off offset:2048 nt
	global_load_dwordx2 v[78:79], v[4:5], off nt
	global_load_dwordx2 v[80:81], v[4:5], off offset:2048 nt
	v_and_b32_e32 v2, 0xfff, v206
	v_cmp_ne_u32_e64 s[6:7], 0, v2
	v_mov_b64_e32 v[86:87], v[90:91]
	v_mov_b64_e32 v[84:85], v[90:91]
	s_and_saveexec_b64 s[4:5], s[6:7]
	s_cbranch_execz .LBB0_280
	global_load_dwordx2 v[84:85], v[0:1], off offset:-4096 nt
	global_load_dwordx2 v[86:87], v[0:1], off offset:-2048 nt
.LBB0_280:
	s_or_b64 exec, exec, s[4:5]
	v_cmp_lt_u32_e64 s[4:5], 1, v2
	v_mov_b64_e32 v[98:99], v[90:91]
	s_and_saveexec_b64 s[12:13], s[4:5]
	s_cbranch_execz .LBB0_282
	v_add_co_u32_e32 v2, vcc, 0xffffc000, v0
	s_nop 1
	v_addc_co_u32_e32 v3, vcc, -1, v1, vcc
	v_add_co_u32_e32 v4, vcc, 0xffffd000, v0
	s_nop 1
	v_addc_co_u32_e32 v5, vcc, -1, v1, vcc
	global_load_dwordx2 v[98:99], v[2:3], off nt
	global_load_dwordx2 v[90:91], v[4:5], off offset:-2048 nt
.LBB0_282:
	s_or_b64 exec, exec, s[12:13]
	v_add_co_u32_e32 v2, vcc, 0x1000, v0
	v_mov_b32_e32 v152, v153
	s_nop 0
	v_addc_co_u32_e32 v3, vcc, 0, v1, vcc
	v_add_co_u32_e32 v4, vcc, 0x2000, v0
	v_mov_b64_e32 v[112:113], v[152:153]
	s_nop 0
	v_addc_co_u32_e32 v5, vcc, 0, v1, vcc
	global_load_dwordx2 v[104:105], v[2:3], off offset:2560 nt
	global_load_dwordx2 v[106:107], v[4:5], off offset:512 nt
	global_load_dwordx2 v[108:109], v[4:5], off offset:2560 nt
	v_mov_b64_e32 v[110:111], v[152:153]
	s_and_saveexec_b64 s[12:13], s[6:7]
	s_cbranch_execz .LBB0_284
	global_load_dwordx2 v[110:111], v[0:1], off offset:-3584 nt
	global_load_dwordx2 v[112:113], v[0:1], off offset:-1536 nt
.LBB0_284:
	s_or_b64 exec, exec, s[12:13]
	v_mov_b64_e32 v[116:117], v[152:153]
	v_mov_b64_e32 v[114:115], v[152:153]
	s_and_saveexec_b64 s[12:13], s[4:5]
	s_cbranch_execz .LBB0_286
	v_add_co_u32_e32 v2, vcc, 0xffffd000, v0
	s_nop 1
	v_addc_co_u32_e32 v3, vcc, -1, v1, vcc
	global_load_dwordx2 v[114:115], v[2:3], off offset:-3584 nt
	global_load_dwordx2 v[116:117], v[2:3], off offset:-1536 nt
.LBB0_286:
	s_or_b64 exec, exec, s[12:13]
	v_add_co_u32_e32 v2, vcc, 0x1000, v0
	v_mov_b32_e32 v152, v153
	s_nop 0
	v_addc_co_u32_e32 v3, vcc, 0, v1, vcc
	v_add_co_u32_e32 v4, vcc, 0x2000, v0
	v_mov_b64_e32 v[126:127], v[152:153]
	s_nop 0
	v_addc_co_u32_e32 v5, vcc, 0, v1, vcc
	global_load_dwordx2 v[118:119], v[2:3], off offset:3072 nt
	global_load_dwordx2 v[120:121], v[4:5], off offset:1024 nt
	global_load_dwordx2 v[122:123], v[4:5], off offset:3072 nt
	v_mov_b64_e32 v[124:125], v[152:153]
	s_and_saveexec_b64 s[12:13], s[6:7]
	s_cbranch_execz .LBB0_288
	global_load_dwordx2 v[124:125], v[0:1], off offset:-3072 nt
	global_load_dwordx2 v[126:127], v[0:1], off offset:-1024 nt
.LBB0_288:
	s_or_b64 exec, exec, s[12:13]
	v_mov_b64_e32 v[130:131], v[152:153]
	v_mov_b64_e32 v[128:129], v[152:153]
	s_and_saveexec_b64 s[12:13], s[4:5]
	s_cbranch_execz .LBB0_290
	v_add_co_u32_e32 v2, vcc, 0xffffd000, v0
	s_nop 1
	v_addc_co_u32_e32 v3, vcc, -1, v1, vcc
	global_load_dwordx2 v[128:129], v[2:3], off offset:-3072 nt
	global_load_dwordx2 v[130:131], v[2:3], off offset:-1024 nt
.LBB0_290:
	s_or_b64 exec, exec, s[12:13]
	v_add_co_u32_e32 v2, vcc, 0x1000, v0
	v_mov_b32_e32 v152, v153
	s_nop 0
	v_addc_co_u32_e32 v3, vcc, 0, v1, vcc
	v_add_co_u32_e32 v4, vcc, 0x2000, v0
	v_mov_b64_e32 v[140:141], v[152:153]
	s_nop 0
	v_addc_co_u32_e32 v5, vcc, 0, v1, vcc
	global_load_dwordx2 v[132:133], v[2:3], off offset:3584 nt
	global_load_dwordx2 v[134:135], v[4:5], off offset:1536 nt
	global_load_dwordx2 v[136:137], v[4:5], off offset:3584 nt
	v_mov_b64_e32 v[138:139], v[152:153]
	s_and_saveexec_b64 s[12:13], s[6:7]
	s_cbranch_execz .LBB0_292
	global_load_dwordx2 v[138:139], v[0:1], off offset:-2560 nt
	global_load_dwordx2 v[140:141], v[0:1], off offset:-512 nt
.LBB0_292:
	s_or_b64 exec, exec, s[12:13]
	v_mov_b32_e32 v161, 0
	v_mov_b32_e32 v160, 0
	v_mov_b32_e32 v163, 0
	v_mov_b32_e32 v162, 0
	s_and_saveexec_b64 s[6:7], s[4:5]
	s_cbranch_execz .LBB0_275
	v_add_co_u32_e32 v0, vcc, 0xffffd000, v0
	s_nop 1
	v_addc_co_u32_e32 v1, vcc, -1, v1, vcc
	global_load_dwordx2 v[160:161], v[0:1], off offset:-2560 nt
	global_load_dwordx2 v[162:163], v[0:1], off offset:-512 nt
	s_branch .LBB0_275
